# gate-column MFMA block moved to the start of the projection phase (xb still cache-resident)
# baseline (speedup 1.0000x reference)
;     __device__ bool next(int i, pg8::Unit& u) const { if (!base.next(i >> 1, u)) return false; u.seg = i & 1; return true; }
; template <class Epi, class Sched, bool ALIGN_EPI = false, bool SP2 = false>
; __device__ __forceinline__ void gemm_phase(PG8_LAS unsigned char* lds, const Gemm g, const Sched& S, const Epi& E) {
;     ...
;     Unit cur, nxt; int ui = 0;
;     if (!S.next(0, cur)) return;
;     __device__ __forceinline__ void operator()(const f32x4 (&acc)[2][2][4][2], const pg8::Unit& u, int wr, int wc, int fr, int fq) const {
;     ...
;                     for (int m = 0; m < 4; ++m) { float* gp = gates + (size_t)(row0 + ai * 128 + m * 16) * 16 + 8 * fq;
;                         *(f32x4*)gp = acc[ai][0][m][0]; *(f32x4*)(gp + 4) = acc[ai][0][m][1]; }
.LBB0_121:
	v_readlane_b32 s0, v246, 12
	v_readlane_b32 s1, v246, 13
	s_cmp_lt_i32 s0, 2
	v_readlane_b32 s2, v246, 14
	v_readlane_b32 s3, v246, 15
	s_cselect_b64 s[0:1], -1, 0
	s_and_b64 s[2:3], s[0:1], s[4:5]
	s_andn2_b64 vcc, exec, s[2:3]
	s_cbranch_vccnz .LBB0_158
	v_readlane_b32 s2, v246, 0
	s_cmpk_gt_i32 s2, 0x15ff
	v_readfirstlane_b32 s7, v144
	v_readlane_b32 s3, v246, 1
	s_cbranch_scc1 .LBB0_158
	v_readlane_b32 s36, v246, 10
	v_readlane_b32 s37, v246, 11
	v_readlane_b32 s38, v246, 0
	v_readfirstlane_b32 s39, v144
	v_and_b32_e32 v0, 15, v144
	v_bfe_u32 v1, v144, 4, 2
	v_lshlrev_b32_e32 v2, 6, v0
	v_lshlrev_b32_e32 v0, 12, v0
	v_lshl_or_b32 v0, v1, 4, v0
	v_lshl_or_b32 v2, v1, 4, v2
	s_lshr_b32 s39, s39, 6
	s_lshl_b32 s38, s38, 3
	s_add_i32 s38, s38, s39
	s_lshl_b32 s40, s34, 3
	s_add_u32 s42, s36, 0x2d00000
	s_addc_u32 s43, s37, 0

; #define PG8_STAGE(bufoff, gbase, voff) do { _Pragma("unroll") for (int _i = 0; _i < 2; ++_i) \
;         __builtin_amdgcn_global_load_lds((const unsigned*)((const char*)(gbase) + (voff)[_i]), (PG8_LAS unsigned*)(lds + (bufoff) + ldsw + _i * 8192), 16, 0, 0); } while (0)
; #define PG8_WAIT_V(n) asm volatile("s_waitcnt vmcnt(" #n ")" ::: "memory")
; #define PG8_BAR __builtin_amdgcn_s_barrier()
;     __device__ bool next(int i, pg8::Unit& u) const { if (!base.next(i >> 1, u)) return false; u.seg = i & 1; return true; }
; template <class Epi, class Sched, bool ALIGN_EPI = false, bool SP2 = false>
; __device__ __forceinline__ void gemm_phase(PG8_LAS unsigned char* lds, const Gemm g, const Sched& S, const Epi& E) {
;     ...
;     for (int i = 0; i < 2; ++i) { int R, C; stage_rc(tid * 16 + i * 8192, R, C); const int Rb = Epi::PERM ? ((R & ~31) + perm32(R & 31)) : R;
;         voffA[i] = (unsigned)(R * K + C) * 2u; voffB[i] = (unsigned)(Rb * K + C) * 2u; }
;     const size_t kstep = (size_t)(BK * 2);
;     const size_t hstep = (size_t)HALF * K * 2;
;     const size_t tstep = 2 * hstep;
;     const unsigned ldsw = (unsigned)wid * 1024u;
;     const int aoff = lds_byte(wr * 64 + fr, fq * 8), boff = lds_byte(wc * 32 + fr, fq * 8);
;     ...
;     Unit cur, nxt; int ui = 0;
;     if (!S.next(0, cur)) return;
;     f32x4 acc[2][2][4][2];
; #pragma unroll
;     for (int a = 0; a < 2; ++a)
; #pragma unroll
;         for (int b = 0; b < 2; ++b)
; #pragma unroll
;             for (int m = 0; m < 4; ++m)
; #pragma unroll
;                 for (int n = 0; n < 2; ++n) acc[a][b][m][n] = (f32x4){0.f, 0.f, 0.f, 0.f};
;     bf16x8 At[4][2], B0[2][2], B1[2][2];
;     const char* cA = (const char*)(cur.seg ? g.A2 : g.A) + (size_t)cur.pm * tstep; const char* cB = (const char*)(cur.seg ? g.Bt2 : g.Bt) + (size_t)cur.pn * tstep;
;     S.a_ready(cur);
;     if constexpr (SP2) {
;         PG8_STAGE(PG8_SB(0, 0), cB, voffB); PG8_STAGE(PG8_SB(0, 1), cB + hstep, voffB); PG8_STAGE(PG8_SA(0, 0), cA, voffA); PG8_STAGE(PG8_SA(0, 1), cA + hstep, voffA);
;         if (wr == 1) PG8_BAR;
;         PG8_WAIT_V(2); PG8_BAR;
;         PG8_STAGE(PG8_SB(1, 0), cB + kstep, voffB); PG8_STAGE(PG8_SA(1, 0), cA + kstep, voffA); PG8_STAGE(PG8_SB(1, 1), cB + hstep + kstep, voffB);
;         PG8_WAIT_V(6); PG8_BAR;
.Lgate_done:
	v_lshrrev_b32_e32 v0, 5, v144
	v_lshrrev_b32_e32 v2, 1, v144
	v_readlane_b32 s2, v246, 10
	v_and_b32_e32 v0, 4, v0
	v_bfe_u32 v1, v144, 2, 2
	v_and_b32_e32 v2, 24, v2
	v_readlane_b32 s3, v246, 11
	s_add_u32 s35, s2, 0x8800000
	v_or3_b32 v0, v0, v1, v2
	v_lshlrev_b32_e32 v1, 4, v144
	s_addc_u32 s54, s3, 0
	s_waitcnt vmcnt(1)
	v_add_u32_e32 v8, 0x2000, v1
	s_add_u32 s55, s2, 0x100000
	v_lshrrev_b32_e32 v2, 7, v8
	s_movk_i32 s2, 0xe0
	v_and_b32_e32 v4, 32, v144
	v_and_or_b32 v3, v2, s2, v0
	v_bitop3_b32 v9, v1, v4, 48 bitop3:0x6c
	v_and_b32_e32 v10, 64, v144
	v_bfe_u32 v11, v144, 2, 4
	s_movk_i32 s2, 0xf0
	v_or_b32_e32 v1, v9, v10
	v_and_or_b32 v2, v2, s2, v11
	v_lshl_or_b32 v130, v2, 12, v1
	v_lshrrev_b32_e32 v2, 3, v144
	s_movk_i32 s2, 0x60
	v_and_or_b32 v0, v2, s2, v0
	s_movk_i32 s2, 0x70
	s_addc_u32 s56, s3, 0
	v_lshl_or_b32 v132, v0, 12, v1
	v_and_or_b32 v0, v2, s2, v11
	v_readlane_b32 s2, v246, 0
	s_ashr_i32 s58, s2, 31
	s_mov_b32 s4, s2
	s_lshr_b32 s2, s58, 29
	v_readlane_b32 s3, v246, 1
	s_add_i32 s2, s4, s2
	s_lshr_b32 s12, s7, 6
	s_ashr_i32 s3, s2, 3
	s_and_b32 s2, s2, -8
	s_lshr_b32 s14, s7, 8
	s_lshl_b32 s57, s12, 10
	s_sub_i32 s2, s4, s2
	s_cmp_lt_i32 s2, 0
	s_movk_i32 s59, 0x2c1
	s_cselect_b32 s4, s59, 0x2c0
	s_mul_i32 s2, s2, s4
	s_add_i32 s2, s2, s3
	s_mul_hi_i32 s3, s2, 0xba2e8ba4
	s_add_i32 s3, s3, s2
	s_lshr_b32 s4, s3, 31
	s_ashr_i32 s3, s3, 8
	s_add_i32 s3, s3, s4
	s_lshl_b32 s4, s3, 3
	s_mulk_i32 s3, 0x160
	s_sub_i32 s2, s2, s3
	s_sext_i32_i16 s3, s2
	s_bfe_u32 s3, s3, 0x3001c
	s_add_i32 s3, s2, s3
	s_sext_i32_i16 s5, s3
	s_and_b32 s3, s3, 0xfff8
	s_sub_i32 s2, s2, s3
	s_sext_i32_i16 s2, s2
	s_lshr_b32 s6, s5, 3
	s_add_i32 s46, s4, s2
	s_ashr_i32 s47, s46, 31
	s_bfe_i64 s[4:5], s[6:7], 0x100000
	s_lshl_b64 s[2:3], s[46:47], 20
	s_lshl_b64 s[4:5], s[4:5], 20
	s_add_u32 s50, s55, s4
	s_addc_u32 s51, s56, s5
	s_add_i32 s60, s57, 0
	s_add_i32 m0, s60, 0x10000
	v_lshl_or_b32 v128, v3, 12, v1
	global_load_lds_dwordx4 v132, s[50:51]
	s_add_i32 m0, s60, 0x12000
	s_add_u32 s4, s50, 0x80000
	global_load_lds_dwordx4 v128, s[50:51]
	s_addc_u32 s5, s51, 0
	s_add_i32 m0, s60, 0x14000
	v_lshl_or_b32 v134, v0, 12, v1
	global_load_lds_dwordx4 v132, s[4:5]
	s_add_i32 m0, s60, 0x16000
	s_add_u32 s48, s35, s2
	s_addc_u32 s49, s54, s3
	s_add_i32 s61, s60, 0x2000
	global_load_lds_dwordx4 v128, s[4:5]
	s_mov_b32 m0, s60
	s_add_u32 s2, s48, 0x80000
	global_load_lds_dwordx4 v134, s[48:49]
	s_mov_b32 m0, s61
	s_addc_u32 s3, s49, 0
	s_add_i32 s62, s60, 0x4000
	global_load_lds_dwordx4 v130, s[48:49]
	s_mov_b32 m0, s62
	s_add_i32 s63, s60, 0x6000
	global_load_lds_dwordx4 v134, s[2:3]
	s_mov_b32 m0, s63
	v_mov_b32_e32 v133, 0
	global_load_lds_dwordx4 v130, s[2:3]
	v_mov_b32_e32 v129, v133
	v_mov_b32_e32 v135, v133
	v_mov_b32_e32 v131, v133
	s_cmp_eq_u32 s14, 1
	s_mov_b32 s64, 0
	v_lshl_add_u64 v[6:7], s[50:51], 0, v[132:133]
	v_lshl_add_u64 v[4:5], s[50:51], 0, v[128:129]
	v_lshl_add_u64 v[0:1], s[48:49], 0, v[134:135]
	s_cselect_b64 s[2:3], -1, 0
	s_cmp_lg_u32 s14, 1
	v_lshl_add_u64 v[2:3], s[48:49], 0, v[130:131]
	s_cbranch_scc1 .LBB0_125
	s_barrier
